# mixer-B next-step tile loads pipelined + P5 K-loop head fix + barrier/setprio reorder; code delta padded to 256B multiple
# speedup vs baseline: 1.0012x; 1.0012x over previous
; __device__ __forceinline__ void mixer_b_unit(const Args& a, LAS unsigned char* lds, int unit) {
;     ...
;     f32x2 ba2[2], bx2[2], spl2[2], spy2[2];
; #pragma unroll
;     for (int e = 0; e < 4; ++e) { const int col = OC + 16 * cb + 4 * fq + e; const float sp = -8.0f * log1pf(expf(-a.in[13][col]));
;         ba2[e >> 1][e & 1] = -1.4426950409f * a.in[10][col]; bx2[e >> 1][e & 1] = -1.4426950409f * a.in[12][col]; spl2[e >> 1][e & 1] = 1.4426950409f * sp; spy2[e >> 1][e & 1] = 2.0f * sp; }
.LBB0_623:
	s_or_b64 exec, exec, s[2:3]
	s_waitcnt vmcnt(2)
	v_mul_f32_e32 v4, 0xbfb8aa3b, v74
	v_rndne_f32_e32 v5, v4
	v_sub_f32_e32 v86, v4, v5
	v_fma_f32 v4, v74, s20, -v4
	v_fmac_f32_e32 v4, 0xb2a5705f, v74
	v_add_f32_e32 v4, v86, v4
	s_mul_i32 s0, s12, 0x1980
	s_bfe_u32 s1, s42, 0x30005
	v_exp_f32_e32 v4, v4
	v_cvt_i32_f32_e32 v5, v5
	s_add_i32 s4, s0, 0
	s_lshr_b32 s0, s42, 5
	s_lshl_b32 s3, s1, 13
	s_and_b32 s5, s16, 31
	s_lshl_b32 s8, s1, 14
	s_lshl_b32 s1, s42, 17
	s_and_b32 s2, s1, 0x1800000
	s_lshl_b32 s1, s5, 6
	s_lshl_b32 s0, s0, 11
	s_or_b32 s0, s0, s1
	s_mov_b32 s1, 0x42ce8ed0
	s_lshl_b32 s9, s5, 8
	s_lshl_b32 s10, s5, 9
	v_ldexp_f32 v4, v4, v5
	v_cmp_nlt_f32_e32 vcc, s1, v74
	s_mov_b32 s5, 0xc2b17218
	s_mov_b32 s6, 0x3f2aaaab
	v_cndmask_b32_e32 v4, 0, v4, vcc
	v_cmp_ngt_f32_e32 vcc, s5, v74
	s_waitcnt vmcnt(0)
	v_pk_mul_f32 v[124:125], v[70:71], s[20:21] op_sel_hi:[1,0]
	s_and_b32 s11, s0, 0xf00
	v_cndmask_b32_e32 v110, v139, v4, vcc
	v_add_f32_e32 v74, 1.0, v110
	v_add_f32_e32 v4, -1.0, v74
	v_sub_f32_e32 v5, v4, v74
	v_add_f32_e32 v5, 1.0, v5
	v_sub_f32_e32 v4, v110, v4
	v_add_f32_e32 v86, v4, v5
	v_mul_f32_e32 v4, 0xbfb8aa3b, v75
	v_rndne_f32_e32 v5, v4
	v_sub_f32_e32 v87, v4, v5
	v_fma_f32 v4, v75, s20, -v4
	v_fmac_f32_e32 v4, 0xb2a5705f, v75
	v_add_f32_e32 v4, v87, v4
	v_exp_f32_e32 v87, v4
	v_cvt_i32_f32_e32 v88, v5
	v_cvt_f64_f32_e32 v[4:5], v74
	v_frexp_exp_i32_f64_e32 v90, v[4:5]
	v_cmp_nlt_f32_e32 vcc, s1, v75
	v_ldexp_f32 v4, v87, v88
	v_frexp_mant_f32_e32 v89, v74
	v_cndmask_b32_e32 v4, 0, v4, vcc
	v_cmp_ngt_f32_e32 vcc, s5, v75
	s_mov_b32 s0, 0x3ecc95a3
	s_mov_b32 s18, 0x3e9b6dac
	v_cndmask_b32_e32 v111, v139, v4, vcc
	v_add_f32_e32 v75, 1.0, v111
	v_add_f32_e32 v4, -1.0, v75
	v_sub_f32_e32 v5, v4, v75
	v_add_f32_e32 v5, 1.0, v5
	v_sub_f32_e32 v4, v111, v4
	v_add_f32_e32 v87, v4, v5
	v_frexp_mant_f32_e32 v88, v75
	v_cvt_f64_f32_e32 v[4:5], v75
	v_frexp_exp_i32_f64_e32 v91, v[4:5]
	v_cmp_gt_f32_e32 vcc, s6, v88
	v_pk_mul_f32 v[4:5], v[66:67], s[20:21] op_sel_hi:[1,0]
	s_mov_b32 s24, 0x3f2aaada
	v_subbrev_co_u32_e32 v100, vcc, 0, v91, vcc
	v_cmp_gt_f32_e32 vcc, s6, v89
	v_sub_u32_e32 v71, 0, v100
	s_mov_b32 s28, 0x3f317218
	v_subbrev_co_u32_e32 v101, vcc, 0, v90, vcc
	v_sub_u32_e32 v67, 0, v101
	v_ldexp_f32 v66, v74, v67
	v_ldexp_f32 v70, v86, v67
	v_ldexp_f32 v67, v75, v71
	v_pk_add_f32 v[74:75], v[66:67], 1.0 op_sel_hi:[1,0]
	v_ldexp_f32 v71, v87, v71
	v_pk_add_f32 v[86:87], v[74:75], -1.0 op_sel_hi:[1,0]
	v_pk_add_f32 v[92:93], v[66:67], -1.0 op_sel_hi:[1,0]
	v_pk_add_f32 v[86:87], v[66:67], v[86:87] neg_lo:[0,1] neg_hi:[0,1]
	v_pk_add_f32 v[94:95], v[92:93], 1.0 op_sel_hi:[1,0]
	v_pk_add_f32 v[86:87], v[70:71], v[86:87]
	v_pk_add_f32 v[66:67], v[66:67], v[94:95] neg_lo:[0,1] neg_hi:[0,1]
	v_pk_add_f32 v[88:89], v[74:75], v[86:87]
	v_pk_add_f32 v[66:67], v[70:71], v[66:67]
	v_rcp_f32_e32 v90, v88
	v_rcp_f32_e32 v91, v89
	v_pk_add_f32 v[70:71], v[92:93], v[66:67]
	v_pk_add_f32 v[74:75], v[74:75], v[88:89] neg_lo:[0,1] neg_hi:[0,1]
	v_pk_add_f32 v[92:93], v[92:93], v[70:71] neg_lo:[0,1] neg_hi:[0,1]
	v_pk_add_f32 v[74:75], v[86:87], v[74:75]
	v_pk_mul_f32 v[86:87], v[70:71], v[90:91]
	v_pk_add_f32 v[66:67], v[66:67], v[92:93]
	v_pk_mul_f32 v[92:93], v[88:89], v[86:87]
	s_mov_b32 s30, 0xb102e308
	v_pk_fma_f32 v[94:95], v[86:87], v[88:89], v[92:93] neg_lo:[0,0,1] neg_hi:[0,0,1]
	s_mov_b32 s7, 0x33800000
	v_pk_fma_f32 v[94:95], v[86:87], v[74:75], v[94:95]
	s_mov_b32 s34, 0xc1000000
	v_pk_add_f32 v[96:97], v[92:93], v[94:95]
	v_pk_mul_f32 v[130:131], v[68:69], s[20:21] op_sel_hi:[1,0]
	v_pk_add_f32 v[98:99], v[70:71], v[96:97] neg_lo:[0,1] neg_hi:[0,1]
	v_pk_add_f32 v[92:93], v[96:97], v[92:93] neg_lo:[0,1] neg_hi:[0,1]
	v_pk_add_f32 v[70:71], v[70:71], v[98:99] neg_lo:[0,1] neg_hi:[0,1]
	v_pk_mul_f32 v[132:133], v[72:73], s[20:21] op_sel_hi:[1,0]
	v_pk_add_f32 v[70:71], v[70:71], v[96:97] neg_lo:[0,1] neg_hi:[0,1]
	v_lshlrev_b32_e32 v81, 3, v79
	v_pk_add_f32 v[66:67], v[66:67], v[70:71]
	v_pk_add_f32 v[70:71], v[92:93], v[94:95] neg_lo:[0,1] neg_hi:[0,1]
	v_and_b32_e32 v2, 63, v78
	v_pk_add_f32 v[66:67], v[70:71], v[66:67]
	s_add_i32 s4, s4, 0x11a00
	v_pk_add_f32 v[70:71], v[98:99], v[66:67]
	v_and_b32_e32 v157, 7, v78
	v_pk_mul_f32 v[92:93], v[90:91], v[70:71]
	v_lshrrev_b32_e32 v159, 2, v2
	v_pk_mul_f32 v[94:95], v[88:89], v[92:93]
	s_and_b32 s16, s16, 3
	v_pk_fma_f32 v[88:89], v[92:93], v[88:89], v[94:95] neg_lo:[0,0,1] neg_hi:[0,0,1]
	s_waitcnt lgkmcnt(0)
; __device__ __forceinline__ void mixer_b_unit(const Args& a, LAS unsigned char* lds, int unit) {
;     ...
;     for (int e = 0; e < 4; ++e) { const int col = OC + 16 * cb + 4 * fq + e; const float sp = -8.0f * log1pf(expf(-a.in[13][col]));
;         ba2[e >> 1][e & 1] = -1.4426950409f * a.in[10][col]; bx2[e >> 1][e & 1] = -1.4426950409f * a.in[12][col]; spl2[e >> 1][e & 1] = 1.4426950409f * sp; spy2[e >> 1][e & 1] = 2.0f * sp; }
	s_add_i32 s3, s12, s3
	v_pk_fma_f32 v[74:75], v[92:93], v[74:75], v[88:89]
	v_pk_add_f32 v[88:89], v[98:99], v[70:71] neg_lo:[0,1] neg_hi:[0,1]
	s_lshl_b32 s17, s12, 1
	v_pk_add_f32 v[66:67], v[66:67], v[88:89]
	v_pk_add_f32 v[88:89], v[94:95], v[74:75]
	s_add_i32 s48, s3, s9
	v_pk_add_f32 v[96:97], v[70:71], v[88:89] neg_lo:[0,1] neg_hi:[0,1]
	v_pk_add_f32 v[94:95], v[88:89], v[94:95] neg_lo:[0,1] neg_hi:[0,1]
	v_pk_add_f32 v[70:71], v[70:71], v[96:97] neg_lo:[0,1] neg_hi:[0,1]
	s_or_b32 s3, s8, s10
	v_pk_add_f32 v[70:71], v[70:71], v[88:89] neg_lo:[0,1] neg_hi:[0,1]
	v_cvt_f32_i32_e32 v89, v100
	v_pk_add_f32 v[66:67], v[66:67], v[70:71]
	v_pk_add_f32 v[70:71], v[94:95], v[74:75] neg_lo:[0,1] neg_hi:[0,1]
	v_cvt_f32_i32_e32 v88, v101
	v_pk_add_f32 v[66:67], v[70:71], v[66:67]
	v_pk_add_f32 v[70:71], v[86:87], v[92:93]
	v_pk_add_f32 v[66:67], v[96:97], v[66:67]
	v_pk_add_f32 v[74:75], v[70:71], v[86:87] neg_lo:[0,1] neg_hi:[0,1]
	v_pk_mul_f32 v[66:67], v[90:91], v[66:67]
	v_pk_add_f32 v[74:75], v[92:93], v[74:75] neg_lo:[0,1] neg_hi:[0,1]
	v_mov_b64_e32 v[90:91], s[0:1]
	v_pk_add_f32 v[66:67], v[74:75], v[66:67]
	v_pk_mul_f32 v[94:95], v[88:89], s[28:29] op_sel_hi:[1,0]
	v_pk_add_f32 v[74:75], v[70:71], v[66:67]
	v_pk_fma_f32 v[96:97], v[88:89], s[28:29], v[94:95] op_sel_hi:[1,0,1] neg_lo:[0,0,1] neg_hi:[0,0,1]
	v_pk_mul_f32 v[86:87], v[74:75], v[74:75]
	v_pk_add_f32 v[70:71], v[74:75], v[70:71] neg_lo:[0,1] neg_hi:[0,1]
	v_pk_fma_f32 v[92:93], v[86:87], s[18:19], v[90:91] op_sel_hi:[1,0,0]
	v_pk_add_f32 v[66:67], v[66:67], v[70:71] neg_lo:[0,1] neg_hi:[0,1]
	v_ldexp_f32 v70, v74, 1
	v_pk_fma_f32 v[92:93], v[86:87], v[92:93], s[24:25] op_sel_hi:[1,1,0]
	v_ldexp_f32 v71, v75, 1
	v_pk_mul_f32 v[74:75], v[74:75], v[86:87]
	v_ldexp_f32 v99, v67, 1
	v_pk_mul_f32 v[74:75], v[74:75], v[92:93]
	v_ldexp_f32 v66, v66, 1
	v_pk_add_f32 v[86:87], v[70:71], v[74:75]
	v_mov_b32_e32 v67, v99
	v_pk_add_f32 v[70:71], v[86:87], v[70:71] neg_lo:[0,1] neg_hi:[0,1]
	v_pk_fma_f32 v[88:89], v[88:89], s[30:31], v[96:97] op_sel_hi:[1,0,1]
	v_pk_add_f32 v[70:71], v[74:75], v[70:71] neg_lo:[0,1] neg_hi:[0,1]
	v_pk_add_f32 v[96:97], v[94:95], v[88:89]
	v_pk_add_f32 v[92:93], v[66:67], v[70:71]
	v_mov_b32_e32 v75, v71
	v_mov_b32_e32 v67, v93
	v_mov_b32_e32 v71, v87
	v_mov_b32_e32 v74, v94
	v_mov_b32_e32 v98, v88
	v_pk_add_f32 v[66:67], v[66:67], v[70:71]
	v_pk_add_f32 v[70:71], v[86:87], v[92:93]
	v_pk_add_f32 v[74:75], v[74:75], v[98:99]
	v_mov_b32_e32 v98, v96
	v_mov_b32_e32 v99, v95
	v_mov_b32_e32 v100, v70
	v_mov_b32_e32 v101, v89
	v_mov_b32_e32 v104, v96
	v_mov_b32_e32 v105, v87
	v_mov_b32_e32 v106, v70
	v_mov_b32_e32 v107, v93
	v_pk_add_f32 v[102:103], v[98:99], v[100:101]
	v_pk_add_f32 v[104:105], v[104:105], v[106:107]
	v_pk_add_f32 v[106:107], v[96:97], v[70:71]
	v_pk_add_f32 v[98:99], v[102:103], v[98:99] neg_lo:[0,1] neg_hi:[0,1]
	v_mov_b32_e32 v102, v70
	v_mov_b32_e32 v103, v107
	v_mov_b32_e32 v108, v86
	v_mov_b32_e32 v109, v97
	v_pk_add_f32 v[102:103], v[102:103], v[108:109] neg_lo:[0,1] neg_hi:[0,1]
	v_mov_b32_e32 v108, v96
	v_mov_b32_e32 v109, v107
	v_mov_b32_e32 v95, v103
	v_pk_add_f32 v[94:95], v[108:109], v[94:95] neg_lo:[0,1] neg_hi:[0,1]
	v_pk_add_f32 v[100:101], v[100:101], v[98:99] neg_lo:[0,1] neg_hi:[0,1]
	v_mov_b32_e32 v108, v94
	v_mov_b32_e32 v109, v99
	v_mov_b32_e32 v99, v87
	v_pk_add_f32 v[108:109], v[88:89], v[108:109] neg_lo:[0,1] neg_hi:[0,1]
	v_pk_add_f32 v[98:99], v[104:105], v[98:99] neg_lo:[0,1] neg_hi:[0,1]
	v_mov_b32_e32 v89, v97
	v_pk_add_f32 v[70:71], v[70:71], v[86:87] neg_lo:[0,1] neg_hi:[0,1]
	v_pk_add_f32 v[74:75], v[74:75], v[98:99] neg_lo:[0,1] neg_hi:[0,1]
	v_pk_add_f32 v[86:87], v[88:89], v[94:95] neg_lo:[0,1] neg_hi:[0,1]
	v_pk_add_f32 v[66:67], v[66:67], v[102:103] neg_lo:[0,1] neg_hi:[0,1]
	v_pk_add_f32 v[70:71], v[92:93], v[70:71] neg_lo:[0,1] neg_hi:[0,1]
	v_pk_add_f32 v[88:89], v[66:67], v[86:87]
	v_mov_b32_e32 v67, v75
	v_pk_add_f32 v[92:93], v[100:101], v[74:75]
	v_pk_add_f32 v[66:67], v[108:109], v[66:67]
	v_mov_b32_e32 v87, v101
	v_pk_add_f32 v[66:67], v[66:67], v[86:87] neg_lo:[0,1] neg_hi:[0,1]
	v_mov_b32_e32 v74, v88
	v_mov_b32_e32 v75, v93
	v_pk_add_f32 v[74:75], v[74:75], v[66:67] neg_lo:[0,1] neg_hi:[0,1]
	v_pk_add_f32 v[66:67], v[70:71], v[66:67] neg_lo:[0,1] neg_hi:[0,1]
	v_pk_add_f32 v[74:75], v[86:87], v[74:75] neg_lo:[0,1] neg_hi:[0,1]
	v_pk_add_f32 v[70:71], v[92:93], v[88:89]
	v_pk_add_f32 v[66:67], v[66:67], v[74:75]
	v_pk_add_f32 v[74:75], v[106:107], v[70:71]
	s_mov_b32 s0, 0x7f800000
	v_pk_add_f32 v[86:87], v[74:75], v[106:107] neg_lo:[0,1] neg_hi:[0,1]
	v_cmp_neq_f32_e32 vcc, s0, v110
	v_pk_add_f32 v[70:71], v[70:71], v[86:87] neg_lo:[0,1] neg_hi:[0,1]
	v_mov_b32_e32 v156, 0
	v_pk_add_f32 v[66:67], v[66:67], v[70:71]
	v_mul_f32_e32 v70, 0xbfb8aa3b, v76
	v_rndne_f32_e32 v71, v70
	v_pk_add_f32 v[66:67], v[74:75], v[66:67]
	v_sub_f32_e32 v74, v70, v71
	v_fma_f32 v70, v76, s20, -v70
	v_fmac_f32_e32 v70, 0xb2a5705f, v76
	v_cndmask_b32_e32 v66, v139, v66, vcc
	v_cmp_neq_f32_e32 vcc, s0, v111
	v_add_f32_e32 v70, v74, v70
	v_exp_f32_e32 v70, v70
	v_cndmask_b32_e32 v67, v139, v67, vcc
	v_cmp_lt_f32_e64 vcc, |v111|, s7
	v_cvt_i32_f32_e32 v71, v71
	v_and_b32_e32 v138, 14, v159
	v_cndmask_b32_e32 v67, v67, v111, vcc
	v_cmp_lt_f32_e64 vcc, |v110|, s7
	s_mov_b32 s23, s26
	v_or_b32_e32 v160, 16, v159
	v_cndmask_b32_e32 v66, v66, v110, vcc
	v_pk_mul_f32 v[66:67], v[66:67], s[34:35] op_sel_hi:[1,0]
	v_cmp_nlt_f32_e32 vcc, s1, v76
	v_pk_add_f32 v[126:127], v[66:67], v[66:67]
	v_pk_mul_f32 v[128:129], v[66:67], s[74:75] op_sel_hi:[1,0]
	v_ldexp_f32 v66, v70, v71
	v_cndmask_b32_e32 v66, 0, v66, vcc
	v_cmp_ngt_f32_e32 vcc, s5, v76
	s_lshl_b32 s49, s48, 5
	s_add_i32 s50, s3, s17
	v_cndmask_b32_e32 v102, v139, v66, vcc
	v_add_f32_e32 v70, 1.0, v102
	v_add_f32_e32 v66, -1.0, v70
	v_sub_f32_e32 v67, v66, v70
	v_add_f32_e32 v67, 1.0, v67
	v_sub_f32_e32 v66, v102, v66
	v_add_f32_e32 v71, v66, v67
	v_mul_f32_e32 v66, 0xbfb8aa3b, v77
	v_rndne_f32_e32 v67, v66
	v_sub_f32_e32 v74, v66, v67
	v_fma_f32 v66, v77, s20, -v66
	v_fmac_f32_e32 v66, 0xb2a5705f, v77
	v_add_f32_e32 v66, v74, v66
	v_exp_f32_e32 v74, v66
	v_cvt_i32_f32_e32 v75, v67
	v_cvt_f64_f32_e32 v[66:67], v70
	v_frexp_exp_i32_f64_e32 v86, v[66:67]
	v_cmp_nlt_f32_e32 vcc, s1, v77
	v_ldexp_f32 v66, v74, v75
	v_frexp_mant_f32_e32 v76, v70
	v_cndmask_b32_e32 v66, 0, v66, vcc
	v_cmp_ngt_f32_e32 vcc, s5, v77
	s_mov_b64 s[86:87], 0
	s_mov_b32 s51, 61
	v_cndmask_b32_e32 v103, v139, v66, vcc
	v_add_f32_e32 v74, 1.0, v103
	v_add_f32_e32 v66, -1.0, v74
	v_sub_f32_e32 v67, v66, v74
	v_add_f32_e32 v67, 1.0, v67
	v_sub_f32_e32 v66, v103, v66
	v_add_f32_e32 v75, v66, v67
	v_frexp_mant_f32_e32 v77, v74
	v_cvt_f64_f32_e32 v[66:67], v74
	v_frexp_exp_i32_f64_e32 v66, v[66:67]
	v_cmp_gt_f32_e32 vcc, s6, v77
	s_waitcnt lgkmcnt(0)
	s_barrier
; __device__ __forceinline__ void mixer_b_unit(const Args& a, LAS unsigned char* lds, int unit) {
;     ...
;     for (int e = 0; e < 4; ++e) { const int col = OC + 16 * cb + 4 * fq + e; const float sp = -8.0f * log1pf(expf(-a.in[13][col]));
;         ba2[e >> 1][e & 1] = -1.4426950409f * a.in[10][col]; bx2[e >> 1][e & 1] = -1.4426950409f * a.in[12][col]; spl2[e >> 1][e & 1] = 1.4426950409f * sp; spy2[e >> 1][e & 1] = 2.0f * sp; }
	v_subbrev_co_u32_e32 v96, vcc, 0, v66, vcc
	v_cmp_gt_f32_e32 vcc, s6, v76
	v_sub_u32_e32 v69, 0, v96
	s_nop 0
	v_subbrev_co_u32_e32 v97, vcc, 0, v86, vcc
	v_sub_u32_e32 v67, 0, v97
	v_ldexp_f32 v66, v70, v67
	v_ldexp_f32 v68, v71, v67
	v_ldexp_f32 v67, v74, v69
	v_pk_add_f32 v[70:71], v[66:67], 1.0 op_sel_hi:[1,0]
	v_ldexp_f32 v69, v75, v69
	v_pk_add_f32 v[72:73], v[70:71], -1.0 op_sel_hi:[1,0]
	v_pk_add_f32 v[86:87], v[66:67], -1.0 op_sel_hi:[1,0]
	v_pk_add_f32 v[72:73], v[66:67], v[72:73] neg_lo:[0,1] neg_hi:[0,1]
	v_pk_add_f32 v[88:89], v[86:87], 1.0 op_sel_hi:[1,0]
	v_pk_add_f32 v[72:73], v[68:69], v[72:73]
	v_pk_add_f32 v[66:67], v[66:67], v[88:89] neg_lo:[0,1] neg_hi:[0,1]
	v_pk_add_f32 v[74:75], v[70:71], v[72:73]
	v_pk_add_f32 v[66:67], v[68:69], v[66:67]
	v_rcp_f32_e32 v76, v74
	v_rcp_f32_e32 v77, v75
	v_pk_add_f32 v[68:69], v[86:87], v[66:67]
	v_pk_add_f32 v[70:71], v[70:71], v[74:75] neg_lo:[0,1] neg_hi:[0,1]
	v_pk_add_f32 v[86:87], v[86:87], v[68:69] neg_lo:[0,1] neg_hi:[0,1]
	v_pk_add_f32 v[70:71], v[72:73], v[70:71]
	v_pk_mul_f32 v[72:73], v[68:69], v[76:77]
	v_pk_add_f32 v[66:67], v[66:67], v[86:87]
	v_pk_mul_f32 v[86:87], v[74:75], v[72:73]
	v_cmp_neq_f32_e32 vcc, s0, v102
	v_pk_fma_f32 v[88:89], v[72:73], v[74:75], v[86:87] neg_lo:[0,0,1] neg_hi:[0,0,1]
	s_nop 0
	v_pk_fma_f32 v[88:89], v[72:73], v[70:71], v[88:89]
	s_nop 0
	v_pk_add_f32 v[92:93], v[86:87], v[88:89]
	s_nop 0
	v_pk_add_f32 v[94:95], v[68:69], v[92:93] neg_lo:[0,1] neg_hi:[0,1]
	v_pk_add_f32 v[86:87], v[92:93], v[86:87] neg_lo:[0,1] neg_hi:[0,1]
	v_pk_add_f32 v[68:69], v[68:69], v[94:95] neg_lo:[0,1] neg_hi:[0,1]
	s_nop 0
	v_pk_add_f32 v[68:69], v[68:69], v[92:93] neg_lo:[0,1] neg_hi:[0,1]
	s_nop 0
	v_pk_add_f32 v[66:67], v[66:67], v[68:69]
	v_pk_add_f32 v[68:69], v[86:87], v[88:89] neg_lo:[0,1] neg_hi:[0,1]
	s_nop 0
	v_pk_add_f32 v[66:67], v[68:69], v[66:67]
	s_nop 0
	v_pk_add_f32 v[68:69], v[94:95], v[66:67]
	s_nop 0
	v_pk_mul_f32 v[86:87], v[76:77], v[68:69]
	s_nop 0
	v_pk_mul_f32 v[88:89], v[74:75], v[86:87]
	s_nop 0
	v_pk_fma_f32 v[74:75], v[86:87], v[74:75], v[88:89] neg_lo:[0,0,1] neg_hi:[0,0,1]
	s_nop 0
	v_pk_fma_f32 v[70:71], v[86:87], v[70:71], v[74:75]
	v_pk_add_f32 v[74:75], v[94:95], v[68:69] neg_lo:[0,1] neg_hi:[0,1]
	s_nop 0
	v_pk_add_f32 v[66:67], v[66:67], v[74:75]
	v_pk_add_f32 v[74:75], v[88:89], v[70:71]
	s_nop 0
	v_pk_add_f32 v[92:93], v[68:69], v[74:75] neg_lo:[0,1] neg_hi:[0,1]
	v_pk_add_f32 v[88:89], v[74:75], v[88:89] neg_lo:[0,1] neg_hi:[0,1]
	v_pk_add_f32 v[68:69], v[68:69], v[92:93] neg_lo:[0,1] neg_hi:[0,1]
	s_nop 0
	v_pk_add_f32 v[68:69], v[68:69], v[74:75] neg_lo:[0,1] neg_hi:[0,1]
	s_nop 0
	v_pk_add_f32 v[66:67], v[66:67], v[68:69]
	v_pk_add_f32 v[68:69], v[88:89], v[70:71] neg_lo:[0,1] neg_hi:[0,1]
	s_nop 0
	v_pk_add_f32 v[66:67], v[68:69], v[66:67]
	v_pk_add_f32 v[68:69], v[72:73], v[86:87]
	v_pk_add_f32 v[66:67], v[92:93], v[66:67]
	v_pk_add_f32 v[70:71], v[68:69], v[72:73] neg_lo:[0,1] neg_hi:[0,1]
	v_pk_mul_f32 v[66:67], v[76:77], v[66:67]
	v_pk_add_f32 v[70:71], v[86:87], v[70:71] neg_lo:[0,1] neg_hi:[0,1]
	v_cvt_f32_i32_e32 v73, v96
	v_pk_add_f32 v[66:67], v[70:71], v[66:67]
	v_cvt_f32_i32_e32 v72, v97
	v_pk_add_f32 v[70:71], v[68:69], v[66:67]
	v_pk_mul_f32 v[86:87], v[72:73], s[28:29] op_sel_hi:[1,0]
	v_pk_mul_f32 v[74:75], v[70:71], v[70:71]
	v_pk_add_f32 v[68:69], v[70:71], v[68:69] neg_lo:[0,1] neg_hi:[0,1]
	v_pk_fma_f32 v[76:77], v[74:75], s[18:19], v[90:91] op_sel_hi:[1,0,0]
	v_pk_add_f32 v[66:67], v[66:67], v[68:69] neg_lo:[0,1] neg_hi:[0,1]
	v_ldexp_f32 v68, v70, 1
	v_pk_fma_f32 v[76:77], v[74:75], v[76:77], s[24:25] op_sel_hi:[1,1,0]
	v_ldexp_f32 v69, v71, 1
	v_pk_mul_f32 v[70:71], v[70:71], v[74:75]
	v_ldexp_f32 v91, v67, 1
	v_pk_mul_f32 v[70:71], v[70:71], v[76:77]
	v_ldexp_f32 v66, v66, 1
	v_pk_add_f32 v[74:75], v[68:69], v[70:71]
	v_mov_b32_e32 v67, v91
	v_pk_add_f32 v[68:69], v[74:75], v[68:69] neg_lo:[0,1] neg_hi:[0,1]
	v_pk_fma_f32 v[88:89], v[72:73], s[28:29], v[86:87] op_sel_hi:[1,0,1] neg_lo:[0,0,1] neg_hi:[0,0,1]
	v_pk_add_f32 v[68:69], v[70:71], v[68:69] neg_lo:[0,1] neg_hi:[0,1]
	v_pk_fma_f32 v[72:73], v[72:73], s[30:31], v[88:89] op_sel_hi:[1,0,1]
	v_pk_add_f32 v[76:77], v[66:67], v[68:69]
	v_mov_b32_e32 v71, v69
	v_mov_b32_e32 v67, v77
	v_mov_b32_e32 v69, v75
	v_pk_add_f32 v[88:89], v[86:87], v[72:73]
	v_mov_b32_e32 v70, v86
	v_mov_b32_e32 v90, v72
	v_pk_add_f32 v[66:67], v[66:67], v[68:69]
	v_pk_add_f32 v[68:69], v[74:75], v[76:77]
	v_pk_add_f32 v[70:71], v[70:71], v[90:91]
	v_mov_b32_e32 v90, v88
	v_mov_b32_e32 v91, v87
	v_mov_b32_e32 v92, v68
	v_mov_b32_e32 v93, v73
	v_mov_b32_e32 v96, v88
	v_mov_b32_e32 v97, v75
	v_mov_b32_e32 v98, v68
	v_mov_b32_e32 v99, v77
	v_pk_add_f32 v[94:95], v[90:91], v[92:93]
	v_pk_add_f32 v[96:97], v[96:97], v[98:99]
	v_pk_add_f32 v[98:99], v[88:89], v[68:69]
	v_pk_add_f32 v[90:91], v[94:95], v[90:91] neg_lo:[0,1] neg_hi:[0,1]
	v_mov_b32_e32 v94, v68
	v_mov_b32_e32 v95, v99
	v_mov_b32_e32 v100, v74
	v_mov_b32_e32 v101, v89
	v_pk_add_f32 v[94:95], v[94:95], v[100:101] neg_lo:[0,1] neg_hi:[0,1]
	v_mov_b32_e32 v100, v88
	v_mov_b32_e32 v101, v99
	v_mov_b32_e32 v87, v95
	v_pk_add_f32 v[86:87], v[100:101], v[86:87] neg_lo:[0,1] neg_hi:[0,1]
; #define LAS __attribute__((address_space(3)))
; __device__ __forceinline__ CvtTile cvt_decode(const Args& a, int t) {
;     CvtTile c; c.src = a.in[18]; c.dst = nullptr; c.gain = a.in[17]; c.ldw = 0; c.ldt = 0; c.valid = 0; c.has_gain = 0;
;     if (t < CV_UP) { const int kb = t % (DM / 32), nb = t / (DM / 32); const int n0 = 32 * nb; const int ch = (n0 < FFW) ? n0 : n0 - FFW; const int dn0 = (ch >> 7) * 256 + (ch & 127) + ((n0 < FFW) ? 0 : 128);
;         c.src = a.in[18] + (size_t)(32 * kb) * UPN + n0; c.dst = (bf16*)(a.ws + WS_WUP) + (size_t)dn0 * DM + 32 * kb; c.gain = a.in[17] + 32 * kb; c.ldw = UPN; c.ldt = DM; c.valid = 1; c.has_gain = 1; return c; }
; __device__ __forceinline__ void mixer_b_unit(const Args& a, LAS unsigned char* lds, int unit) {
;     ...
;     for (int e = 0; e < 4; ++e) { const int col = OC + 16 * cb + 4 * fq + e; const float sp = -8.0f * log1pf(expf(-a.in[13][col]));
;         ba2[e >> 1][e & 1] = -1.4426950409f * a.in[10][col]; bx2[e >> 1][e & 1] = -1.4426950409f * a.in[12][col]; spl2[e >> 1][e & 1] = 1.4426950409f * sp; spy2[e >> 1][e & 1] = 2.0f * sp; }
;     const int cg = tid & 31, rg = tid >> 5;
;     LAS float* ctab = (LAS float*)(lds + MB_CTAB);
;     for (int i = tid; i < 5 * LHD; i += NWAVES * 64) { const int k = i >> 8, c = i & 255; ctab[i] = (k < 4) ? a.in[7][(size_t)k * LW + HC + c] : a.in[8][HC + c]; }
;     LAS f32x2* ag = (LAS f32x2*)(lds + MB_AG);
;     LAS unsigned* cscr = (LAS unsigned*)(lds + MB_CVT + wave * (3 * 32 * 17 * 4));
;     const int c8 = lane & 7, rgp = lane >> 3;
;     float carry = 0.f;
;     const bf16* xrp = XR + ((size_t)b * SEQ + 4 * rg) * LW + HC + 8 * cg;
;     u32x4 raw[7];
; #pragma unroll
;     for (int i = 0; i < 7; ++i) raw[i] = (4 * rg - 3 + i >= 0) ? *(const u32x4*)(xrp + (ptrdiff_t)(i - 3) * LW) : (u32x4){0u, 0u, 0u, 0u};
;     const int sidu = (unit * MB_STEPS * NWAVES + wave) * CV_SLOTS;
	v_pk_add_f32 v[92:93], v[92:93], v[90:91] neg_lo:[0,1] neg_hi:[0,1]
	v_mov_b32_e32 v100, v86
	v_mov_b32_e32 v101, v91
	v_mov_b32_e32 v91, v75
	v_pk_add_f32 v[100:101], v[72:73], v[100:101] neg_lo:[0,1] neg_hi:[0,1]
	v_pk_add_f32 v[90:91], v[96:97], v[90:91] neg_lo:[0,1] neg_hi:[0,1]
	v_mov_b32_e32 v73, v89
	v_pk_add_f32 v[70:71], v[70:71], v[90:91] neg_lo:[0,1] neg_hi:[0,1]
	v_pk_add_f32 v[72:73], v[72:73], v[86:87] neg_lo:[0,1] neg_hi:[0,1]
	v_pk_add_f32 v[66:67], v[66:67], v[94:95] neg_lo:[0,1] neg_hi:[0,1]
	v_pk_add_f32 v[68:69], v[68:69], v[74:75] neg_lo:[0,1] neg_hi:[0,1]
	v_pk_add_f32 v[74:75], v[66:67], v[72:73]
	v_mov_b32_e32 v67, v71
	v_pk_add_f32 v[68:69], v[76:77], v[68:69] neg_lo:[0,1] neg_hi:[0,1]
	v_pk_add_f32 v[76:77], v[92:93], v[70:71]
	v_pk_add_f32 v[66:67], v[100:101], v[66:67]
	v_mov_b32_e32 v73, v93
	v_pk_add_f32 v[66:67], v[66:67], v[72:73] neg_lo:[0,1] neg_hi:[0,1]
	v_mov_b32_e32 v70, v74
	v_mov_b32_e32 v71, v77
	v_pk_add_f32 v[70:71], v[70:71], v[66:67] neg_lo:[0,1] neg_hi:[0,1]
	v_pk_add_f32 v[66:67], v[68:69], v[66:67] neg_lo:[0,1] neg_hi:[0,1]
	v_pk_add_f32 v[70:71], v[72:73], v[70:71] neg_lo:[0,1] neg_hi:[0,1]
	v_pk_add_f32 v[68:69], v[76:77], v[74:75]
	v_pk_add_f32 v[66:67], v[66:67], v[70:71]
	v_pk_add_f32 v[70:71], v[98:99], v[68:69]
	v_lshrrev_b32_e32 v74, 1, v2
	v_pk_add_f32 v[72:73], v[70:71], v[98:99] neg_lo:[0,1] neg_hi:[0,1]
	v_and_b32_e32 v74, 28, v74
	v_pk_add_f32 v[68:69], v[68:69], v[72:73] neg_lo:[0,1] neg_hi:[0,1]
	v_and_b32_e32 v76, 3, v78
	v_pk_add_f32 v[66:67], v[66:67], v[68:69]
	v_add_u32_e32 v74, s4, v74
	v_pk_add_f32 v[66:67], v[70:71], v[66:67]
	v_lshl_add_u32 v77, v76, 4, s4
	v_cndmask_b32_e32 v66, v139, v66, vcc
	v_cmp_neq_f32_e32 vcc, s0, v103
	v_readlane_b32 s0, v238, 52
	s_movk_i32 s4, 0x208
	v_cndmask_b32_e32 v67, v139, v67, vcc
	v_cmp_lt_f32_e64 vcc, |v103|, s7
	v_lshl_add_u32 v158, v81, 2, s0
	s_ashr_i32 s0, s14, 3
	v_cndmask_b32_e32 v67, v67, v103, vcc
	v_cmp_lt_f32_e64 vcc, |v102|, s7
	s_andn2_b32 s0, s0, 31
	v_or_b32_e32 v69, s0, v84
	v_cndmask_b32_e32 v66, v66, v102, vcc
	s_lshl_b32 s0, s12, 6
	v_pk_mul_f32 v[66:67], v[66:67], s[34:35] op_sel_hi:[1,0]
	s_add_i32 s0, s0, 0
	v_pk_add_f32 v[134:135], v[66:67], v[66:67]
	v_pk_mul_f32 v[136:137], v[66:67], s[74:75] op_sel_hi:[1,0]
	v_lshlrev_b32_e32 v66, 2, v2
	v_or_b32_e32 v70, s15, v84
	v_lshl_add_u32 v73, v157, 3, s0
	v_cmp_gt_u32_e64 s[0:1], 8, v2
	v_mul_lo_u32 v84, v69, s4
	v_cmp_gt_u32_e64 s[4:5], 16, v2
	v_cmp_gt_u32_e64 s[6:7], 32, v2
	v_lshlrev_b32_e32 v2, 12, v78
	v_and_b32_e32 v2, 0x38000, v2
	v_or_b32_e32 v2, s2, v2
	s_lshl_b32 s24, s12, 3
	v_or_b32_e32 v2, s11, v2
	v_and_b32_e32 v68, 56, v78
	s_ashr_i32 s25, s24, 31
	v_mov_b32_e32 v71, s26
	v_lshl_or_b32 v2, s16, 6, v2
	v_lshl_add_u32 v67, v79, 4, 0
	v_and_b32_e32 v66, 28, v66
	v_mad_u32_u24 v70, v70, s46, v71
	v_or_b32_e32 v71, s13, v85
	v_lshl_add_u32 v72, v85, 3, 0
	v_mul_lo_u32 v79, v80, s46
	v_or_b32_e32 v80, 3, v83
	v_mul_lo_u32 v81, v69, s46
	v_mul_u32_u24_e32 v85, 0x208, v68
	v_lshl_add_u64 v[68:69], s[24:25], 0, v[2:3]
	v_lshl_add_u32 v71, v71, 1, 0
	v_mul_u32_u24_e32 v75, 0x44, v66
	v_lshlrev_b32_e32 v140, 3, v76
	v_mul_u32_u24_e32 v76, 0x44, v159
	v_mul_lo_u32 v80, v80, s46
	v_add_u32_e32 v83, 0, v82
	v_or_b32_e32 v68, v68, v157
	v_lshl_add_u64 v[142:143], v[68:69], 1, s[44:45]
	v_add_u32_e32 v161, v67, v79
	v_add_u32_e32 v162, v67, v80
	v_lshlrev_b32_e32 v144, 2, v66
	v_add_u32_e32 v163, v70, v82
	v_add_u32_e32 v164, v83, v81
	v_add_u32_e32 v165, v71, v81
	v_add_u32_e32 v166, v72, v84
	v_add_u32_e32 v167, v73, v85
	v_add_u32_e32 v168, v74, v75
	v_add_u32_e32 v169, v77, v76
	s_cmp_gt_i32 s50, 0x17fff
	s_cselect_b64 s[8:9], -1, 0
	s_mov_b64 s[2:3], -1
	s_and_b64 vcc, exec, s[8:9]
	s_cbranch_vccnz .Lpre_627
	s_ashr_i32 s2, s50, 31
	s_lshr_b32 s2, s2, 25
	s_add_i32 s2, s50, s2
	s_ashr_i32 s3, s2, 7
	s_and_b32 s2, s2, 0xffffff80
	s_sub_i32 s11, s50, s2
	s_lshl_b32 s2, s3, 5
	s_add_i32 s3, s2, 0xffffd000
	s_cmp_lt_i32 s50, 0xc000
	s_cselect_b32 s3, s2, s3
	s_cselect_b32 s10, 0, 0x80
	s_lshl_b32 s12, s3, 1
	s_and_b32 s3, s3, 0x60
	s_and_b32 s12, s12, 0xffffff00
	s_or_b32 s3, s3, s10
	s_or_b32 s10, s3, s12
	s_lshl_b32 s12, s11, 5
	v_readlane_b32 s52, v238, 28
	s_ashr_i32 s13, s12, 31
	s_mul_i32 s11, s11, 0x300000
	v_readlane_b32 s56, v238, 32
	s_mul_hi_i32 s3, s12, 0x18000
	v_readlane_b32 s57, v238, 33
	s_add_u32 s11, s56, s11
	s_addc_u32 s14, s57, s3
	s_ashr_i32 s3, s2, 31
	s_lshl_b64 s[2:3], s[2:3], 2
	s_add_u32 s30, s11, s2
	s_addc_u32 s31, s14, s3
	s_ashr_i32 s11, s10, 31
	s_lshl_b64 s[2:3], s[10:11], 13
	s_add_u32 s10, s21, s2
	s_addc_u32 s11, s75, s3
	s_lshl_b64 s[2:3], s[12:13], 1
	s_add_u32 s88, s10, s2
	v_readlane_b32 s54, v238, 30
	s_addc_u32 s89, s11, s3
	s_lshl_b64 s[2:3], s[12:13], 2
	v_readlane_b32 s55, v238, 31
	s_add_u32 s12, s54, s2
	s_addc_u32 s13, s55, s3
	s_mov_b64 s[2:3], 0
	v_readlane_b32 s53, v238, 29
	v_readlane_b32 s58, v238, 34
	v_readlane_b32 s59, v238, 35
	v_readlane_b32 s60, v238, 36
	v_readlane_b32 s61, v238, 37
	v_readlane_b32 s62, v238, 38
	v_readlane_b32 s63, v238, 39
	v_readlane_b32 s64, v238, 40
	v_readlane_b32 s65, v238, 41
	v_readlane_b32 s66, v238, 42
	v_readlane_b32 s67, v238, 43

; #define LAS __attribute__((address_space(3)))
; __device__ __forceinline__ CvtTile cvt_decode(const Args& a, int t) {
;     CvtTile c; c.src = a.in[18]; c.dst = nullptr; c.gain = a.in[17]; c.ldw = 0; c.ldt = 0; c.valid = 0; c.has_gain = 0;
;     if (t < CV_UP) { const int kb = t % (DM / 32), nb = t / (DM / 32); const int n0 = 32 * nb; const int ch = (n0 < FFW) ? n0 : n0 - FFW; const int dn0 = (ch >> 7) * 256 + (ch & 127) + ((n0 < FFW) ? 0 : 128);
;         c.src = a.in[18] + (size_t)(32 * kb) * UPN + n0; c.dst = (bf16*)(a.ws + WS_WUP) + (size_t)dn0 * DM + 32 * kb; c.gain = a.in[17] + 32 * kb; c.ldw = UPN; c.ldt = DM; c.valid = 1; c.has_gain = 1; return c; }
; __device__ __forceinline__ void mixer_b_unit(const Args& a, LAS unsigned char* lds, int unit) {
;     ...
;     for (int step = 0; step < MB_STEPS; ++step) {
;         const int t0 = step * MBT; const size_t rowbase = (size_t)b * SEQ + t0;
;         const bool more = step + 1 < MB_STEPS;
;         { f32x4 cw[5][2];
; #pragma unroll
;           for (int k = 0; k < 5; ++k) { cw[k][0] = *(const LAS f32x4*)(ctab + k * LHD + 8 * cg); cw[k][1] = *(const LAS f32x4*)(ctab + k * LHD + 8 * cg + 4); }
; #pragma unroll
;           for (int r = 0; r < 4; ++r) { float o[8];
; #pragma unroll
;               for (int j = 0; j < 8; ++j) o[j] = cw[4][j >> 2][j & 3];
; #pragma unroll
;               for (int k = 0; k < 4; ++k) { const u32x4 w = raw[r + k];
;                   o[0] += cw[k][0][0] * bf_lo(w.x); o[1] += cw[k][0][1] * bf_hi(w.x); o[2] += cw[k][0][2] * bf_lo(w.y); o[3] += cw[k][0][3] * bf_hi(w.y);
;                   o[4] += cw[k][1][0] * bf_lo(w.z); o[5] += cw[k][1][1] * bf_hi(w.z); o[6] += cw[k][1][2] * bf_lo(w.w); o[7] += cw[k][1][3] * bf_hi(w.w); }
;               u32x4 p; p.x = cvt_pk_bf16(o[0], o[1]); p.y = cvt_pk_bf16(o[2], o[3]); p.z = cvt_pk_bf16(o[4], o[5]); p.w = cvt_pk_bf16(o[6], o[7]);
;               *(LAS u32x4*)(lds + MB_XC + (4 * rg + r) * MB_XPITCH + 16 * cg) = p; } }
;         const size_t gb = (rowbase + 8 * rgp) * LW + OC + 8 * wave + c8;
;         unsigned short yr[8];
; #pragma unroll
;         for (int i = 0; i < 8; ++i) yr[i] = GYR[gb + (size_t)i * LW];
;         { const int tn = more ? t0 + MBT : t0;
; #pragma unroll
;           for (int i = 0; i < 7; ++i) raw[i] = *(const u32x4*)(xrp + (ptrdiff_t)(tn + i - 3) * LW); }
;         f32x4 cvA[4], cvB[4], cvC[4]; f32x2c glA[2], glB[2], glC[2];
.Lpre_663:
	v_readlane_b32 s52, v238, 28
	v_readlane_b32 s56, v238, 32
	v_readlane_b32 s57, v238, 33
	s_mov_b64 s[70:71], 0
	s_mov_b64 s[16:17], -1
	s_mov_b64 s[28:29], 0
	v_readlane_b32 s53, v238, 29
	v_readlane_b32 s54, v238, 30
	v_readlane_b32 s55, v238, 31
	v_readlane_b32 s58, v238, 34
	v_readlane_b32 s59, v238, 35
	v_readlane_b32 s60, v238, 36
	v_readlane_b32 s61, v238, 37
	v_readlane_b32 s62, v238, 38
	v_readlane_b32 s63, v238, 39
	v_readlane_b32 s64, v238, 40
	v_readlane_b32 s65, v238, 41
	v_readlane_b32 s66, v238, 42
	v_readlane_b32 s67, v238, 43
	s_mov_b64 s[38:39], s[56:57]
	s_andn2_b64 vcc, exec, s[26:27]
	s_mov_b64 s[26:27], s[70:71]
	s_cbranch_vccz .Lpre_650
	s_branch .Lpre_651
	s_nop 0
	s_nop 0
	s_nop 0
	s_nop 0
	s_nop 0
	s_nop 0
	s_nop 0
	s_nop 0
	s_nop 0
	s_nop 0
	s_nop 0
	s_nop 0
	s_nop 0
	s_nop 0
	s_nop 0
	s_nop 0
	s_nop 0
	s_nop 0
	s_nop 0
	s_nop 0
	s_nop 0
	s_nop 0
	s_nop 0
	s_nop 0
	s_nop 0
	s_nop 0
	s_nop 0
	s_nop 0
	s_nop 0
	s_nop 0
.LBB0_624:
	s_add_i32 s48, s48, 8
	s_addk_i32 s49, 0x100
	s_add_i32 s50, s50, 16
	s_add_u32 s86, s86, 0x80000
	s_waitcnt lgkmcnt(0)
	v_fmac_f32_e32 v114, v156, v115
	s_addc_u32 s87, s87, 0
	s_add_i32 s51, s51, 64
	s_cmp_lg_u32 s86, 0x1000000
	v_mov_b32_e32 v156, v114
	s_cbranch_scc0 .LBB0_593
	s_cmp_gt_i32 s50, 0x17fff
	s_cselect_b64 s[8:9], -1, 0
	s_mov_b64 s[2:3], -1
	s_and_b64 vcc, exec, s[8:9]
	s_cbranch_vccnz .LBB0_627
	s_ashr_i32 s2, s50, 31
	s_lshr_b32 s2, s2, 25
	s_add_i32 s2, s50, s2
	s_ashr_i32 s3, s2, 7
	s_and_b32 s2, s2, 0xffffff80
	s_sub_i32 s11, s50, s2
	s_lshl_b32 s2, s3, 5
	s_add_i32 s3, s2, 0xffffd000
	s_cmp_lt_i32 s50, 0xc000
	s_cselect_b32 s3, s2, s3
	s_cselect_b32 s10, 0, 0x80
	s_lshl_b32 s12, s3, 1
	s_and_b32 s3, s3, 0x60
	s_and_b32 s12, s12, 0xffffff00
	s_or_b32 s3, s3, s10
	s_or_b32 s10, s3, s12
	s_lshl_b32 s12, s11, 5
	v_readlane_b32 s52, v238, 28
	s_ashr_i32 s13, s12, 31
	s_mul_i32 s11, s11, 0x300000
	v_readlane_b32 s56, v238, 32
	s_mul_hi_i32 s3, s12, 0x18000
	v_readlane_b32 s57, v238, 33
	s_add_u32 s11, s56, s11
	s_addc_u32 s14, s57, s3
	s_ashr_i32 s3, s2, 31
	s_lshl_b64 s[2:3], s[2:3], 2
	s_add_u32 s30, s11, s2
	s_addc_u32 s31, s14, s3
	s_ashr_i32 s11, s10, 31
	s_lshl_b64 s[2:3], s[10:11], 13
	s_add_u32 s10, s21, s2
	s_addc_u32 s11, s75, s3
	s_lshl_b64 s[2:3], s[12:13], 1
	s_add_u32 s88, s10, s2
	v_readlane_b32 s54, v238, 30
	s_addc_u32 s89, s11, s3
	s_lshl_b64 s[2:3], s[12:13], 2
	v_readlane_b32 s55, v238, 31
	s_add_u32 s12, s54, s2
	s_addc_u32 s13, s55, s3
	s_mov_b64 s[2:3], 0
	v_readlane_b32 s53, v238, 29
	v_readlane_b32 s58, v238, 34
	v_readlane_b32 s59, v238, 35
	v_readlane_b32 s60, v238, 36
	v_readlane_b32 s61, v238, 37
	v_readlane_b32 s62, v238, 38
	v_readlane_b32 s63, v238, 39
	v_readlane_b32 s64, v238, 40
	v_readlane_b32 s65, v238, 41
	v_readlane_b32 s66, v238, 42
	v_readlane_b32 s67, v238, 43
